# fox early-exit bound tightened from 2^-160 to 2^-64 of the softmax denominator (below f32 resolution of every accumulator)
# speedup vs baseline: 1.0227x; 1.0227x over previous
; template<int MODE,int THRL> __device__ __forceinline__ void attn_unit(int b,int h,int qb,const bf16*Q,const bf16*__restrict__ K,const bf16*__restrict__ V,bf16*O,char*shm,const float*__restrict__ cs2,const float*__restrict__ relb,float kmx){
;     ...
;     if constexpr(MODE==0){ if(t>=3){ const float Bn=-*(const __attribute__((address_space(3))) float*)(shm3+LDS_X+(64*(NT-3-t)+63)*4); const bool c_=(ub+Bn-mhat)<-160.f; const bool a_=__all(c_); if(lane==0)votes[wid]=a_?1u:0u; } }
.LBB0_260:
	s_add_i32 s52, s51, -5
	s_waitcnt lgkmcnt(14)
	v_mfma_f32_32x32x16_bf16 v[20:35], v[128:131], v[136:139], v[20:35]
	v_exp_f32_e32 v36, v36
	v_exp_f32_e32 v37, v37
	v_exp_f32_e32 v38, v38
	v_exp_f32_e32 v39, v39
	s_waitcnt lgkmcnt(12)
	v_mfma_f32_32x32x16_bf16 v[4:19], v[128:131], v[84:87], v[4:19]
	v_exp_f32_e32 v40, v40
	v_exp_f32_e32 v41, v41
	v_exp_f32_e32 v42, v42
	v_exp_f32_e32 v43, v43
	v_add_u32_e32 v0, s2, v231
	ds_read_b128 v[164:167], v0
	ds_read_b128 v[160:163], v0 offset:512
	s_waitcnt lgkmcnt(12)
	v_mfma_f32_32x32x16_bf16 v[20:35], v[124:127], v[88:91], v[20:35]
	v_exp_f32_e32 v44, v44
	v_exp_f32_e32 v45, v45
	v_exp_f32_e32 v46, v46
	v_exp_f32_e32 v47, v47
	ds_read_b128 v[156:159], v0 offset:2048
	ds_read_b128 v[152:155], v0 offset:2560
	s_waitcnt lgkmcnt(12)
	v_mfma_f32_32x32x16_bf16 v[4:19], v[124:127], v[92:95], v[4:19]
	v_exp_f32_e32 v48, v48
	v_exp_f32_e32 v49, v49
	v_exp_f32_e32 v50, v50
	v_exp_f32_e32 v51, v51
	ds_read_b128 v[148:151], v0 offset:4096
	ds_read_b128 v[144:147], v0 offset:4608
	s_waitcnt lgkmcnt(12)
	v_mfma_f32_32x32x16_bf16 v[20:35], v[120:123], v[96:99], v[20:35]
	v_exp_f32_e32 v52, v52
	v_exp_f32_e32 v53, v53
	v_exp_f32_e32 v54, v54
	v_exp_f32_e32 v55, v55
	ds_read_b128 v[140:143], v0 offset:6144
	ds_read_b128 v[136:139], v0 offset:6656
	s_waitcnt lgkmcnt(12)
	v_mfma_f32_32x32x16_bf16 v[4:19], v[120:123], v[68:71], v[4:19]
	v_exp_f32_e32 v56, v56
	v_exp_f32_e32 v57, v57
	v_exp_f32_e32 v58, v58
	v_exp_f32_e32 v59, v59
	s_waitcnt lgkmcnt(10)
	v_mfma_f32_32x32x16_bf16 v[20:35], v[116:119], v[72:75], v[20:35]
	v_exp_f32_e32 v60, v60
	v_exp_f32_e32 v61, v61
	v_exp_f32_e32 v62, v62
	v_exp_f32_e32 v63, v63
	s_waitcnt lgkmcnt(8)
	v_mfma_f32_32x32x16_bf16 v[4:19], v[116:119], v[76:79], v[4:19]
	v_exp_f32_e32 v64, v64
	v_exp_f32_e32 v65, v65
	v_exp_f32_e32 v66, v66
	v_exp_f32_e32 v67, v67
	v_add_u32_e32 v0, 0x1c400, v180
	v_add_u32_e32 v1, 0x1c480, v180
	ds_read_b32 v180, v0
	ds_read_b32 v181, v1
	s_cmp_gt_u32 s52, 2
	s_cselect_b64 s[60:61], -1, 0
	s_cmp_lt_u32 s52, 3
	s_cselect_b64 s[58:59], -1, 0
	s_and_b64 vcc, exec, s[58:59]
	s_cbranch_vccnz .LBB0_264
	s_add_i32 s26, s28, 0x1c4fc
	v_mov_b32_e32 v0, s26
	ds_read_b32 v0, v0
	s_mov_b32 s26, 0xc2800000
	s_mov_b64 s[62:63], exec
	s_waitcnt lgkmcnt(0)
	v_sub_f32_e32 v0, v183, v0
	v_sub_f32_e32 v0, v0, v232
	v_cmp_gt_f32_e32 vcc, s26, v0
	s_and_saveexec_b64 s[64:65], s[44:45]
	s_cmp_eq_u64 vcc, s[62:63]
	s_cselect_b64 s[62:63], -1, 0
	v_cndmask_b32_e64 v0, 0, 1, s[62:63]
	v_mov_b32_e32 v1, s22
	ds_write_b32 v1, v0
	s_or_b64 exec, exec, s[64:65]
